# attention K/V staging thread-to-piece remap (lanes 4-7 of each 8-lane group stage the neighbouring key row): V ds_write_b128 no longer 2-way bank conflicted
# baseline (speedup 1.0000x reference)
; __device__ __forceinline__ int tidx() { int t = threadIdx.x; asm volatile("" : "+v"(t)); return t; }
; __device__ __forceinline__ void attn_dv256_body(const bf16* __restrict__ Qb, const bf16* __restrict__ Kh, const bf16* __restrict__ Vh,
;                                                 float* __restrict__ Ob, int seq, float kmax, char* lds) {
;     ...
;   const int tid = tidx(), wid = tid >> 6, lane = tid & 63, r32 = lane & 31, hi = lane >> 5;
;   const int rg = wid & 3, kh = wid >> 2;
;   char* V_lds = lds; char* K_lds = lds + 65536; char* XCH = lds + 98304; float* LI = (float*)(lds + 131072);
;   f32x16 o[4] = {}; bf16x8 qr[8];
;   const bf16* Qw = Qb + (long)(rg * 32 + r32) * LDQ + hi * 8;
; #pragma unroll
;   for (int d0 = 0; d0 < 8; ++d0) qr[d0] = St::ld8(Qw + d0 * 16);
;   float qq = 0.f;
; #pragma unroll
;   for (int d0 = 0; d0 < 8; ++d0)
; #pragma unroll
;     for (int e = 0; e < 8; ++e) { const float v = __uint_as_float(((unsigned)(unsigned short)qr[d0][e]) << 16); qq += v * v; }
;   qq += __shfl_xor(qq, 32);
;   constexpr float C = SCALE * 1.4426950408889634f;
;   const float mC = -sqrtf(qq) * kmax * C * 1.002f;
.LBB0_909:
	s_mul_i32 s7, s84, 0x4080
	s_mul_hi_u32 s1, s84, 0x4080
	s_add_u32 s7, s78, s7
	s_addc_u32 s1, s79, s1
	s_lshl_b32 s22, s34, 7
	s_ashr_i32 s23, s22, 31
	s_lshl_b64 s[38:39], s[22:23], 1
	s_add_u32 s42, s7, s38
	s_addc_u32 s43, s1, s39
	s_lshl_b32 s0, s0, 1
	s_add_u32 s7, s78, s0
	s_addc_u32 s13, s79, 0
	s_add_u32 s0, s7, s38
	s_addc_u32 s1, s13, s39
	s_add_u32 s38, s0, 0x2800
	s_addc_u32 s39, s1, 0
	s_and_b32 s0, s22, 0xffffff00
	s_ashr_i32 s1, s0, 31
	s_lshl_b64 s[0:1], s[0:1], 1
	s_add_u32 s0, s7, s0
	s_addc_u32 s1, s13, s1
	s_add_u32 s40, s0, 0x3000
	s_addc_u32 s41, s1, 0
	s_ashr_i32 s35, s34, 31
	s_lshl_b64 s[0:1], s[34:35], 2
	s_add_u32 s0, s20, s0
	s_addc_u32 s1, s21, s1
	v_mov_b32_e32 v3, v170
	global_load_dword v6, v165, s[0:1]
	s_mov_b64 s[0:1], 0x2000
	v_ashrrev_i32_e32 v2, 6, v3
	v_lshlrev_b32_e32 v0, 5, v2
	v_and_b32_e32 v186, 31, v3
	v_and_b32_e32 v185, 0x60, v0
	v_or_b32_e32 v0, v185, v186
	v_mul_u32_u24_e32 v0, 0x2040, v0
	v_bfe_u32 v184, v3, 5, 1
	v_lshlrev_b32_e32 v164, 1, v0
	v_lshl_add_u64 v[0:1], s[42:43], 0, v[164:165]
	v_lshlrev_b32_e32 v164, 4, v184
	v_lshl_add_u64 v[0:1], v[0:1], 0, v[164:165]
	v_add_co_u32_e32 v4, vcc, s95, v0
	s_mov_b32 s22, 0xf800000
	s_nop 0
	v_addc_co_u32_e32 v5, vcc, 0, v1, vcc
	global_load_dwordx4 v[80:83], v[4:5], off
	v_lshl_add_u64 v[0:1], v[0:1], 0, s[0:1]
	global_load_dwordx4 v[84:87], v[0:1], off offset:32
	global_load_dwordx4 v[88:91], v[0:1], off offset:64
	global_load_dwordx4 v[92:95], v[0:1], off offset:96
	global_load_dwordx4 v[96:99], v[0:1], off offset:128
	global_load_dwordx4 v[100:103], v[0:1], off offset:160
	global_load_dwordx4 v[104:107], v[0:1], off offset:192
	global_load_dwordx4 v[108:111], v[0:1], off offset:224
	v_ashrrev_i32_e32 v189, 4, v3
	v_add_u32_e32 v190, 32, v189
	s_movk_i32 s13, 0x2040
	s_cmp_lg_u32 0, -1
	v_ashrrev_i32_e32 v187, 8, v3
	v_and_b32_e32 v191, 63, v3
	v_lshlrev_b32_e32 v205, 4, v191
	v_mov_b32_e32 v132, 0
	v_mov_b32_e32 v144, 0
	v_mov_b32_e32 v192, 0
	s_mov_b32 s7, 0
	v_lshlrev_b32_e32 v209, 11, v2
	v_mov_b32_e32 v2, v192
	v_mov_b32_e32 v55, v192
	v_mov_b32_e32 v56, v192
	v_mov_b32_e32 v57, v192
	v_mov_b32_e32 v58, v192
	v_mov_b32_e32 v59, v192
	v_mov_b32_e32 v60, v192
	v_mov_b32_e32 v61, v192
	v_mov_b32_e32 v62, v192
	v_mov_b32_e32 v63, v192
	v_mov_b32_e32 v145, v144
	v_mov_b32_e32 v146, v144
	v_mov_b32_e32 v147, v144
	v_mov_b32_e32 v148, v144
	v_mov_b32_e32 v149, v144
	v_mov_b32_e32 v150, v144
	v_mov_b32_e32 v151, v144
	v_mov_b32_e32 v133, v132
	v_mov_b32_e32 v134, v132
	v_mov_b32_e32 v135, v132
	v_mov_b32_e32 v128, v132
	v_mov_b32_e32 v129, v132
	v_mov_b32_e32 v130, v132
	v_mov_b32_e32 v131, v132
	s_waitcnt vmcnt(8)
	v_mul_f32_e32 v4, 0x4f800000, v6
	v_cmp_gt_f32_e32 vcc, s22, v6
	s_waitcnt vmcnt(6)
	v_lshlrev_b32_e32 v14, 16, v84
	v_cndmask_b32_e32 v4, v6, v4, vcc
	v_sqrt_f32_e32 v7, v4
	v_lshlrev_b32_e32 v8, 16, v81
	v_and_b32_e32 v9, 0xffff0000, v81
	v_lshlrev_b32_e32 v10, 16, v82
	v_add_u32_e32 v0, -1, v7
	v_fma_f32 v1, -v0, v7, v4
	v_add_u32_e32 v5, 1, v7
	v_cmp_ge_f32_e64 s[0:1], 0, v1
	v_and_b32_e32 v1, 0xffff0000, v80
	v_fma_f32 v6, -v5, v7, v4
	v_cndmask_b32_e64 v7, v7, v0, s[0:1]
	v_lshlrev_b32_e32 v0, 16, v80
	v_mul_f32_e32 v54, v1, v1
	v_fmac_f32_e32 v54, v0, v0
	v_fmac_f32_e32 v54, v8, v8
	v_fmac_f32_e32 v54, v9, v9
	v_and_b32_e32 v11, 0xffff0000, v82
	v_fmac_f32_e32 v54, v10, v10
	v_lshlrev_b32_e32 v12, 16, v83
	v_fmac_f32_e32 v54, v11, v11
	v_and_b32_e32 v13, 0xffff0000, v83
	v_fmac_f32_e32 v54, v12, v12
	v_fmac_f32_e32 v54, v13, v13
	v_and_b32_e32 v15, 0xffff0000, v84
	v_fmac_f32_e32 v54, v14, v14
	v_lshlrev_b32_e32 v16, 16, v85
	v_fmac_f32_e32 v54, v15, v15
	v_and_b32_e32 v17, 0xffff0000, v85
	v_fmac_f32_e32 v54, v16, v16
	v_lshlrev_b32_e32 v18, 16, v86
	v_fmac_f32_e32 v54, v17, v17
	v_and_b32_e32 v19, 0xffff0000, v86
	v_fmac_f32_e32 v54, v18, v18
	v_lshlrev_b32_e32 v20, 16, v87
	v_fmac_f32_e32 v54, v19, v19
	v_and_b32_e32 v21, 0xffff0000, v87
	v_fmac_f32_e32 v54, v20, v20
	s_waitcnt vmcnt(5)
	v_lshlrev_b32_e32 v22, 16, v88
	v_fmac_f32_e32 v54, v21, v21
	v_and_b32_e32 v23, 0xffff0000, v88
	v_fmac_f32_e32 v54, v22, v22
	v_lshlrev_b32_e32 v24, 16, v89
	v_fmac_f32_e32 v54, v23, v23
	v_and_b32_e32 v25, 0xffff0000, v89
	v_fmac_f32_e32 v54, v24, v24
	v_lshlrev_b32_e32 v26, 16, v90
	v_fmac_f32_e32 v54, v25, v25
	v_and_b32_e32 v27, 0xffff0000, v90
	v_fmac_f32_e32 v54, v26, v26
	v_lshlrev_b32_e32 v28, 16, v91
	v_fmac_f32_e32 v54, v27, v27
	v_and_b32_e32 v29, 0xffff0000, v91
	v_fmac_f32_e32 v54, v28, v28
	s_waitcnt vmcnt(4)
	v_lshlrev_b32_e32 v30, 16, v92
	v_fmac_f32_e32 v54, v29, v29
	v_and_b32_e32 v31, 0xffff0000, v92
	v_fmac_f32_e32 v54, v30, v30
	v_lshlrev_b32_e32 v32, 16, v93
	v_fmac_f32_e32 v54, v31, v31
	v_and_b32_e32 v33, 0xffff0000, v93
	v_fmac_f32_e32 v54, v32, v32
	v_lshlrev_b32_e32 v34, 16, v94
	v_fmac_f32_e32 v54, v33, v33
	v_and_b32_e32 v35, 0xffff0000, v94
	v_fmac_f32_e32 v54, v34, v34
	v_lshlrev_b32_e32 v36, 16, v95
	v_fmac_f32_e32 v54, v35, v35
	v_and_b32_e32 v37, 0xffff0000, v95
	v_fmac_f32_e32 v54, v36, v36
	s_waitcnt vmcnt(3)
	v_lshlrev_b32_e32 v38, 16, v96
	v_fmac_f32_e32 v54, v37, v37
	v_and_b32_e32 v39, 0xffff0000, v96
	v_fmac_f32_e32 v54, v38, v38
	v_lshlrev_b32_e32 v40, 16, v97
	v_fmac_f32_e32 v54, v39, v39
	v_and_b32_e32 v41, 0xffff0000, v97
	v_fmac_f32_e32 v54, v40, v40
	v_lshlrev_b32_e32 v42, 16, v98
	v_fmac_f32_e32 v54, v41, v41
	v_and_b32_e32 v43, 0xffff0000, v98
	v_fmac_f32_e32 v54, v42, v42
	v_lshlrev_b32_e32 v44, 16, v99
	v_fmac_f32_e32 v54, v43, v43
	v_and_b32_e32 v45, 0xffff0000, v99
	v_fmac_f32_e32 v54, v44, v44
	s_waitcnt vmcnt(2)
; __device__ __forceinline__ int v_st(int k, int c) { const int kk = (k & ~0xC) | ((k & 4) << 1) | ((k & 8) >> 1); return ((kk >> 3) * 4 + (c >> 5)) * 512 + ((kk & 7) * 32 + (c & 31)) * 2; }
; __device__ __forceinline__ int v_rd_base(int lane) { return ((lane & 3) << 3) | (((lane >> 2) & 3) << 6) | (((lane >> 4) & 1) << 5) | (((lane >> 5) & 1) << 8); }
; #define KLOAD(k0) do { kr0 = St::ld8(&Kh[(long)((k0) + sr) * LDK + sc]); kr1 = St::ld8(&Kh[(long)((k0) + 32 + sr) * LDK + sc]); } while (0)
; #define VLOAD(k0) do { vr0 = St::ld8(&Vh[(long)((k0) + sr) * LDK + sc]); vr1 = St::ld8(&Vh[(long)((k0) + 32 + sr) * LDK + sc]); \
;     vr2 = St::ld8(&Vh[(long)((k0) + sr) * LDK + 128 + sc]); vr3 = St::ld8(&Vh[(long)((k0) + 32 + sr) * LDK + 128 + sc]); } while (0)
; #define KWRITE(b) do { *(bf16x8*)(K_lds + (b) * 16384 + KSWZ(sr, sc * 2)) = kr0; *(bf16x8*)(K_lds + (b) * 16384 + KSWZ(32 + sr, sc * 2)) = kr1; } while (0)
; #define VWRITE(b) do { *(bf16x8*)(V_lds + ((b) * 2) * 16384 + vst0) = vr0; *(bf16x8*)(V_lds + ((b) * 2) * 16384 + vst1) = vr1; \
;     *(bf16x8*)(V_lds + ((b) * 2 + 1) * 16384 + vst1) = vr2; *(bf16x8*)(V_lds + ((b) * 2 + 1) * 16384 + vst0) = vr3; } while (0)
; __device__ __forceinline__ void attn_dv256_body(const bf16* __restrict__ Qb, const bf16* __restrict__ Kh, const bf16* __restrict__ Vh,
;                                                 float* __restrict__ Ob, int seq, float kmax, char* lds) {
;     ...
;   const int sr = tid >> 4, sc = (tid & 15) * 8, vst0 = v_st(sr, sc), vst1 = v_st(32 + sr, sc);
;   const int vb0 = (int)(uintptr_t)V_lds + kh * 16384 + v_rd_base(lane);
;   bf16x8 kr0, kr1, vr0, vr1, vr2, vr3;
;     ...
;   const int NT = seq / KVBLK;
;   f32x16 pc, pn; pn = f32x16{};
;   bf16x8 q0 = {}, q1 = {}, q2 = {}, q3 = {};
;   char* XC0 = XCH;
;   KLOAD(0); VLOAD(0); asm volatile("s_waitcnt vmcnt(0)" ::: "memory"); KWRITE(0); VWRITE(0);
;   KLOAD(KVBLK); VLOAD(KVBLK); asm volatile("s_waitcnt vmcnt(0)" ::: "memory"); KWRITE(1); VWRITE(1);
;   __syncthreads();
	v_lshlrev_b32_e32 v46, 16, v100
	v_fmac_f32_e32 v54, v45, v45
	v_and_b32_e32 v47, 0xffff0000, v100
	v_fmac_f32_e32 v54, v46, v46
	v_lshlrev_b32_e32 v48, 16, v101
	v_fmac_f32_e32 v54, v47, v47
	v_and_b32_e32 v49, 0xffff0000, v101
	v_fmac_f32_e32 v54, v48, v48
	v_lshlrev_b32_e32 v50, 16, v102
	v_fmac_f32_e32 v54, v49, v49
	v_lshlrev_b32_e32 v49, 3, v3
	v_and_b32_e32 v51, 0xffff0000, v102
	v_fmac_f32_e32 v54, v50, v50
	v_and_b32_e32 v32, 0x78, v49
	v_mov_b32_e32 v33, v165
	v_lshlrev_b32_e32 v52, 16, v103
	v_fmac_f32_e32 v54, v51, v51
	v_mad_i64_i32 v[8:9], s[0:1], v189, s13, v[32:33]
	v_mad_i64_i32 v[10:11], s[0:1], v190, s13, v[32:33]
	v_and_b32_e32 v53, 0xffff0000, v103
	v_fmac_f32_e32 v54, v52, v52
	v_lshlrev_b64 v[16:17], 1, v[8:9]
	v_lshlrev_b64 v[18:19], 1, v[10:11]
	v_fmac_f32_e32 v54, v53, v53
	s_waitcnt vmcnt(1)
	v_lshlrev_b32_e32 v0, 16, v104
	v_lshl_add_u64 v[8:9], s[38:39], 0, v[16:17]
	v_lshl_add_u64 v[12:13], s[38:39], 0, v[18:19]
	v_fmac_f32_e32 v54, v0, v0
	v_and_b32_e32 v0, 0xffff0000, v104
	v_mad_i64_i32 v[24:25], s[0:1], v189, s13, 0
	v_mad_i64_i32 v[26:27], s[0:1], v190, s13, 0
	global_load_dwordx4 v[8:11], v[8:9], off
	s_nop 0
	global_load_dwordx4 v[12:15], v[12:13], off
	v_add_u32_e32 v34, 64, v189
	v_add_u32_e32 v36, 0x60, v189
	v_fmac_f32_e32 v54, v0, v0
	v_lshlrev_b32_e32 v0, 1, v32
	v_lshl_add_u64 v[24:25], v[24:25], 1, s[40:41]
	v_mov_b32_e32 v1, v165
	v_lshl_add_u64 v[26:27], v[26:27], 1, s[40:41]
	v_mad_i64_i32 v[40:41], s[0:1], v34, s13, 0
	v_mad_i64_i32 v[34:35], s[0:1], v34, s13, v[32:33]
	v_mad_i64_i32 v[32:33], s[0:1], v36, s13, v[32:33]
	v_lshl_add_u64 v[16:17], s[40:41], 0, v[16:17]
	v_lshl_add_u64 v[20:21], s[40:41], 0, v[18:19]
	v_lshl_add_u64 v[24:25], v[24:25], 0, v[0:1]
	v_lshl_add_u64 v[28:29], v[26:27], 0, v[0:1]
	v_lshlrev_b64 v[42:43], 1, v[34:35]
	v_lshlrev_b64 v[46:47], 1, v[32:33]
	global_load_dwordx4 v[16:19], v[16:17], off
	s_nop 0
	global_load_dwordx4 v[20:23], v[20:21], off
	s_nop 0
	global_load_dwordx4 v[24:27], v[24:25], off offset:256
	s_nop 0
	global_load_dwordx4 v[28:31], v[28:29], off offset:256
	s_waitcnt vmcnt(0)
	v_lshl_add_u64 v[34:35], s[38:39], 0, v[42:43]
	v_mad_i64_i32 v[44:45], s[0:1], v36, s13, 0
	v_lshl_add_u64 v[36:37], s[38:39], 0, v[46:47]
	v_lshl_add_u64 v[42:43], s[40:41], 0, v[42:43]
	v_lshl_add_u64 v[40:41], v[40:41], 1, s[40:41]
	global_load_dwordx4 v[32:35], v[34:35], off
	s_nop 0
	global_load_dwordx4 v[36:39], v[36:37], off
	v_lshl_add_u64 v[46:47], s[40:41], 0, v[46:47]
	global_load_dwordx4 v[116:119], v[42:43], off
	global_load_dwordx4 v[112:115], v[46:47], off
	v_lshl_add_u64 v[40:41], v[40:41], 0, v[0:1]
	v_lshl_add_u64 v[42:43], v[44:45], 1, s[40:41]
	v_lshl_add_u64 v[42:43], v[42:43], 0, v[0:1]
	global_load_dwordx4 v[120:123], v[40:41], off offset:256
	global_load_dwordx4 v[124:127], v[42:43], off offset:256
	v_lshlrev_b32_e32 v48, 16, v105
	v_fmac_f32_e32 v54, v48, v48
	v_and_b32_e32 v40, 0xffff0000, v105
	v_fmac_f32_e32 v54, v40, v40
	v_lshlrev_b32_e32 v40, 16, v106
	v_fmac_f32_e32 v54, v40, v40
	v_and_b32_e32 v40, 0xffff0000, v106
	v_fmac_f32_e32 v54, v40, v40
	v_lshlrev_b32_e32 v40, 16, v107
	v_fmac_f32_e32 v54, v40, v40
	v_and_b32_e32 v40, 0xffff0000, v107
	v_and_b32_e32 v41, 0xfffff0, v189
	v_lshlrev_b32_e32 v42, 1, v189
	v_fmac_f32_e32 v54, v40, v40
	s_waitcnt vmcnt(12)
	v_lshlrev_b32_e32 v40, 16, v108
	v_and_or_b32 v41, v42, 8, v41
	v_fmac_f32_e32 v54, v40, v40
	v_and_b32_e32 v40, 0xffff0000, v108
	v_lshrrev_b32_e32 v42, 1, v189
	v_lshrrev_b32_e32 v41, 1, v41
	v_bfe_u32 v43, v49, 5, 2
	v_and_b32_e32 v44, 3, v189
	v_fmac_f32_e32 v54, v40, v40
	v_lshlrev_b32_e32 v40, 16, v109
	v_or_b32_e32 v41, v41, v43
	v_and_or_b32 v42, v42, 4, v44
	v_fmac_f32_e32 v54, v40, v40
	v_and_b32_e32 v40, 0xffff0000, v109
	v_lshlrev_b32_e32 v41, 9, v41
	v_lshlrev_b32_e32 v42, 6, v42
	v_and_b32_e32 v44, 48, v0
	v_fmac_f32_e32 v54, v40, v40
	v_lshlrev_b32_e32 v40, 16, v110
	v_or3_b32 v193, v41, v42, v44
	v_and_b32_e32 v41, 0xfffff0, v190
	v_lshlrev_b32_e32 v45, 1, v190
	v_fmac_f32_e32 v54, v40, v40
	v_and_b32_e32 v40, 0xffff0000, v110
	v_and_or_b32 v41, v45, 8, v41
	v_fmac_f32_e32 v54, v40, v40
	v_lshlrev_b32_e32 v40, 16, v111
	v_lshrrev_b32_e32 v41, 1, v41
	v_fmac_f32_e32 v54, v40, v40
	v_and_b32_e32 v40, 0xffff0000, v111
	v_or_b32_e32 v41, v41, v43
	v_fmac_f32_e32 v54, v40, v40
	v_xor_b32_e32 v40, 32, v171
	v_lshlrev_b32_e32 v41, 9, v41
	v_cmp_lt_i32_e64 s[0:1], v40, v172
	v_or3_b32 v194, v41, v42, v44
	v_lshlrev_b32_e32 v41, 8, v189
	v_and_b32_e32 v42, 0x70, v3
	v_cndmask_b32_e64 v40, v171, v40, s[0:1]
	s_cselect_b32 s13, 0, 0
	v_bfe_u32 v249, v170, 8, 1
	v_lshlrev_b32_e32 v249, 7, v249
	v_bfe_u32 v250, v170, 4, 1
	v_lshlrev_b32_e32 v250, 7, v250
	v_bitop3_b32 v195, v0, v41, v42 bitop3:0xde
	v_xor_b32_e32 v195, v195, v249
	s_add_i32 s0, 0, 0x10000
	v_add_u32_e32 v41, s0, v195
	s_waitcnt vmcnt(11)
	ds_write_b128 v41, v[8:11]
	v_lshlrev_b32_e32 v8, 8, v190
	v_bitop3_b32 v196, v0, v8, v42 bitop3:0xde
	v_xor_b32_e32 v196, v196, v249
	v_add_u32_e32 v8, s0, v196
	s_waitcnt vmcnt(10)
	ds_write_b128 v8, v[12:15]
	v_add_u32_e32 v8, 0, v193
	v_add_u32_e32 v9, 0, v194
	s_add_i32 s1, 0, 0x14000
	s_waitcnt vmcnt(9)
	ds_write_b128 v8, v[16:19]
	s_waitcnt vmcnt(8)
	ds_write_b128 v9, v[20:23]
	s_waitcnt vmcnt(7)
	ds_write_b128 v9, v[24:27] offset:16384
	s_waitcnt vmcnt(6)
	ds_write_b128 v8, v[28:31] offset:16384
	v_add_u32_e32 v10, s1, v195
	s_waitcnt vmcnt(0)
	v_lshlrev_b32_e32 v12, 4, v3
	v_and_b32_e32 v16, 0x70, v12
	v_bitop3_b32 v199, v164, v16, 32 bitop3:0x36
	v_xor_b32_e32 v199, v199, v250
	s_waitcnt vmcnt(5)
	ds_write_b128 v10, v[32:35]
	v_add_u32_e32 v10, s1, v196
	s_waitcnt vmcnt(4)
	ds_write_b128 v10, v[36:39]
	s_waitcnt vmcnt(3)
	ds_write_b128 v8, v[116:119] offset:32768
	s_waitcnt vmcnt(2)
	ds_write_b128 v9, v[112:115] offset:32768
	s_waitcnt vmcnt(1)
	ds_write_b128 v9, v[120:123] offset:49152
	s_waitcnt vmcnt(0)
	ds_write_b128 v8, v[124:127] offset:49152
	v_lshlrev_b32_e32 v8, 13, v187
	v_lshlrev_b32_e32 v9, 8, v186
	v_add3_u32 v197, s0, v8, v9
	s_movk_i32 s0, 0x70
	v_bitop3_b32 v198, v164, v12, s0 bitop3:0x78
	v_xor_b32_e32 v198, v198, v250
	v_add_u32_e32 v8, v197, v198
	s_waitcnt lgkmcnt(0)
	s_barrier
; __device__ __forceinline__ int v_st(int k, int c) { const int kk = (k & ~0xC) | ((k & 4) << 1) | ((k & 8) >> 1); return ((kk >> 3) * 4 + (c >> 5)) * 512 + ((kk & 7) * 32 + (c & 31)) * 2; }
; __device__ __forceinline__ int v_rd_base(int lane) { return ((lane & 3) << 3) | (((lane >> 2) & 3) << 6) | (((lane >> 4) & 1) << 5) | (((lane >> 5) & 1) << 8); }
; #define KLOAD(k0) do { kr0 = St::ld8(&Kh[(long)((k0) + sr) * LDK + sc]); kr1 = St::ld8(&Kh[(long)((k0) + 32 + sr) * LDK + sc]); } while (0)
; #define VLOAD(k0) do { vr0 = St::ld8(&Vh[(long)((k0) + sr) * LDK + sc]); vr1 = St::ld8(&Vh[(long)((k0) + 32 + sr) * LDK + sc]); \
;     vr2 = St::ld8(&Vh[(long)((k0) + sr) * LDK + 128 + sc]); vr3 = St::ld8(&Vh[(long)((k0) + 32 + sr) * LDK + 128 + sc]); } while (0)
; #define KWRITE(b) do { *(bf16x8*)(K_lds + (b) * 16384 + KSWZ(sr, sc * 2)) = kr0; *(bf16x8*)(K_lds + (b) * 16384 + KSWZ(32 + sr, sc * 2)) = kr1; } while (0)
; #define VWRITE(b) do { *(bf16x8*)(V_lds + ((b) * 2) * 16384 + vst0) = vr0; *(bf16x8*)(V_lds + ((b) * 2) * 16384 + vst1) = vr1; \
;     *(bf16x8*)(V_lds + ((b) * 2 + 1) * 16384 + vst1) = vr2; *(bf16x8*)(V_lds + ((b) * 2 + 1) * 16384 + vst0) = vr3; } while (0)
; __device__ __forceinline__ void attn_dv256_body(const bf16* __restrict__ Qb, const bf16* __restrict__ Kh, const bf16* __restrict__ Vh,
;                                                 float* __restrict__ Ob, int seq, float kmax, char* lds) {
;     ...
;   qq += __shfl_xor(qq, 32);
;   constexpr float C = SCALE * 1.4426950408889634f;
;   const float mC = -sqrtf(qq) * kmax * C * 1.002f;
;   float l_reg = 0.f;
;   const int sr = tid >> 4, sc = (tid & 15) * 8, vst0 = v_st(sr, sc), vst1 = v_st(32 + sr, sc);
;   const int vb0 = (int)(uintptr_t)V_lds + kh * 16384 + v_rd_base(lane);
;   bf16x8 kr0, kr1, vr0, vr1, vr2, vr3;
;     ...
;   const int NT = seq / KVBLK;
;   f32x16 pc, pn; pn = f32x16{};
;   bf16x8 q0 = {}, q1 = {}, q2 = {}, q3 = {};
;   char* XC0 = XCH;
;   KLOAD(0); VLOAD(0); asm volatile("s_waitcnt vmcnt(0)" ::: "memory"); KWRITE(0); VWRITE(0);
;   KLOAD(KVBLK); VLOAD(KVBLK); asm volatile("s_waitcnt vmcnt(0)" ::: "memory"); KWRITE(1); VWRITE(1);
;   __syncthreads();
;   QKH(pc, 0);
;   KLOAD((2 < NT ? 2 : NT - 1) * KVBLK);
;   __syncthreads();
	ds_read_b128 v[8:11], v8
	v_cmp_lt_f32_e64 s[0:1], 0, v6
	v_lshlrev_b32_e32 v188, 2, v40
	ds_bpermute_b32 v40, v188, v54
	v_cndmask_b32_e64 v5, v7, v5, s[0:1]
	v_add_u32_e32 v7, v197, v199
	ds_read_b128 v[12:15], v7
	s_waitcnt lgkmcnt(2)
	v_mfma_f32_32x32x16_bf16 v[64:79], v[8:11], v[80:83], 0
	v_mul_f32_e32 v6, 0x37800000, v5
	v_cndmask_b32_e32 v5, v5, v6, vcc
	s_waitcnt lgkmcnt(1)
	v_add_f32_e32 v6, v54, v40
	v_mul_f32_e32 v7, 0x4f800000, v6
	v_cmp_gt_f32_e32 vcc, s22, v6
	v_bitop3_b32 v200, v164, v16, 64 bitop3:0x36
	v_xor_b32_e32 v200, v200, v250
	v_lshlrev_b32_e32 v3, 1, v3
	v_cndmask_b32_e32 v17, v6, v7, vcc
	v_add_u32_e32 v6, v197, v200
	ds_read_b128 v[6:9], v6
	s_waitcnt lgkmcnt(1)
	v_mfma_f32_32x32x16_bf16 v[64:79], v[12:15], v[84:87], v[64:79]
	v_mov_b32_e32 v15, 0x260
	v_cmp_class_f32_e64 s[0:1], v4, v15
	v_sqrt_f32_e32 v18, v17
	v_and_b32_e32 v3, 32, v3
	v_cndmask_b32_e64 v14, v5, v4, s[0:1]
	s_movk_i32 s0, 0x60
	v_bitop3_b32 v201, v164, v16, s0 bitop3:0x36
	v_xor_b32_e32 v201, v201, v250
	v_add_u32_e32 v5, v197, v201
	ds_read_b128 v[10:13], v5
	s_waitcnt lgkmcnt(1)
	v_mfma_f32_32x32x16_bf16 v[64:79], v[6:9], v[88:91], v[64:79]
	v_add_u32_e32 v4, -1, v18
	v_fma_f32 v5, -v4, v18, v17
	v_cmp_ge_f32_e64 s[0:1], 0, v5
	v_add_u32_e32 v9, 1, v18
	v_lshl_add_u64 v[166:167], s[38:39], 0, v[0:1]
	v_cndmask_b32_e64 v8, v18, v4, s[0:1]
	s_movk_i32 s0, 0x80
	v_bitop3_b32 v202, v164, v16, s0 bitop3:0x36
	v_xor_b32_e32 v202, v202, v250
	v_add_u32_e32 v4, v197, v202
	ds_read_b128 v[4:7], v4
	s_waitcnt lgkmcnt(1)
	v_mfma_f32_32x32x16_bf16 v[64:79], v[10:13], v[92:95], v[64:79]
	v_fma_f32 v10, -v9, v18, v17
	v_cmp_lt_f32_e64 s[0:1], 0, v10
	v_lshl_add_u64 v[168:169], s[40:41], 0, v[0:1]
	v_mov_b32_e32 v18, v192
	v_cndmask_b32_e64 v12, v8, v9, s[0:1]
	s_movk_i32 s0, 0xa0
	v_bitop3_b32 v203, v164, v16, s0 bitop3:0x36
	v_xor_b32_e32 v203, v203, v250
	v_add_u32_e32 v8, v197, v203
	ds_read_b128 v[8:11], v8
	s_waitcnt lgkmcnt(1)
	v_mfma_f32_32x32x16_bf16 v[64:79], v[4:7], v[96:99], v[64:79]
	v_mul_f32_e32 v13, 0x37800000, v12
	v_cndmask_b32_e32 v4, v12, v13, vcc
	v_cmp_class_f32_e32 vcc, v17, v15
	s_movk_i32 s0, 0xc0
	v_bitop3_b32 v204, v164, v16, s0 bitop3:0x36
	v_xor_b32_e32 v204, v204, v250
	v_cndmask_b32_e32 v4, v4, v17, vcc
	v_mul_f32_e32 v12, v14, v4
	v_add_u32_e32 v4, v197, v204
	ds_read_b128 v[4:7], v4
	s_waitcnt lgkmcnt(1)
	v_mfma_f32_32x32x16_bf16 v[64:79], v[8:11], v[100:103], v[64:79]
	s_movk_i32 s0, 0xe0
	v_bitop3_b32 v206, v164, v16, s0 bitop3:0x36
	v_xor_b32_e32 v206, v206, v250
	v_add_u32_e32 v8, v197, v206
	v_lshlrev_b32_e32 v14, 3, v191
	ds_read_b128 v[8:11], v8
	v_lshlrev_b32_e32 v13, 14, v187
	v_mul_f32_e32 v12, 0x3e0293ee, v12
	s_waitcnt lgkmcnt(1)
	v_mfma_f32_32x32x16_bf16 v[64:79], v[4:7], v[104:107], v[64:79]
	v_and_b32_e32 v4, 0xc0, v205
	v_and_or_b32 v4, v14, 24, v4
	v_and_b32_e32 v5, 0x100, v14
	v_or3_b32 v3, v4, v3, v5
	v_add3_u32 v207, v13, s13, v3
	v_add_u32_e32 v3, 0x80, v189
	v_mov_b64_e32 v[4:5], s[38:39]
	v_mad_i64_i32 v[6:7], s[22:23], v3, s93, v[4:5]
	v_add_u32_e32 v3, 0xa0, v189
	v_lshl_add_u64 v[6:7], v[6:7], 0, v[0:1]
	v_mad_i64_i32 v[4:5], s[22:23], v3, s93, v[4:5]
	v_lshl_add_u64 v[4:5], v[4:5], 0, v[0:1]
	global_load_dwordx4 v[136:139], v[6:7], off
	global_load_dwordx4 v[140:143], v[4:5], off
	s_waitcnt lgkmcnt(0)
	v_mfma_f32_32x32x16_bf16 v[64:79], v[8:11], v[108:111], v[64:79]
	v_mul_f32_e32 v208, 0xbf804189, v12
	s_add_i32 s0, s6, -1
	v_mov_b32_e32 v0, 0
	v_mov_b32_e32 v1, v192
	v_mov_b32_e32 v3, v192
	v_mov_b32_e32 v4, v192
	v_mov_b32_e32 v5, v192
	v_mov_b32_e32 v6, v192
	v_mov_b32_e32 v7, v192
	v_mov_b32_e32 v8, v192
	v_mov_b32_e32 v9, v192
	v_mov_b32_e32 v10, v192
	v_mov_b32_e32 v11, v192
	v_mov_b32_e32 v12, v192
	v_mov_b32_e32 v13, v192
	v_mov_b32_e32 v14, v192
	v_mov_b32_e32 v15, v192
	v_mov_b32_e32 v16, 0
	v_mov_b32_e32 v17, v192
	v_mov_b32_e32 v19, v192
	v_mov_b32_e32 v20, v192
	v_mov_b32_e32 v21, v192
	v_mov_b32_e32 v22, v192
	v_mov_b32_e32 v23, v192
	v_mov_b32_e32 v24, v192
	v_mov_b32_e32 v25, v192
	v_mov_b32_e32 v26, v192
	v_mov_b32_e32 v27, v192
	v_mov_b32_e32 v28, v192
	v_mov_b32_e32 v29, v192
	v_mov_b32_e32 v30, v192
	v_mov_b32_e32 v31, v192
	v_mov_b32_e32 v32, 0
	v_mov_b32_e32 v33, v192
	v_mov_b32_e32 v34, v192
	v_mov_b32_e32 v35, v192
	v_mov_b32_e32 v36, v192
	v_mov_b32_e32 v37, v192
	v_mov_b32_e32 v38, v192
	v_mov_b32_e32 v39, v192
	v_mov_b32_e32 v40, v192
	v_mov_b32_e32 v41, v192
	v_mov_b32_e32 v42, v192
	v_mov_b32_e32 v43, v192
	v_mov_b32_e32 v44, v192
	v_mov_b32_e32 v45, v192
	v_mov_b32_e32 v46, v192
	v_mov_b32_e32 v47, v192
	v_mov_b32_e32 v48, 0
	v_mov_b32_e32 v49, v192
	v_mov_b32_e32 v50, v192
	v_mov_b32_e32 v51, v192
	v_mov_b32_e32 v52, v192
	v_mov_b32_e32 v53, v192
	v_mov_b32_e32 v54, v192
	s_barrier
	v_bfe_u32 v218, v170, 2, 1
	v_xor_b32_e32 v189, v189, v218
	v_xor_b32_e32 v190, v190, v218
	v_lshlrev_b32_e32 v219, 6, v218
	v_xor_b32_e32 v193, v193, v219
	v_xor_b32_e32 v194, v194, v219
	v_mul_u32_u24_e32 v219, 0x110, v218
	v_xor_b32_e32 v195, v195, v219
	v_xor_b32_e32 v196, v196, v219
	s_min_u32 s100, s0, 2
	s_lshl_b32 s100, s100, 6
	v_add_u32_e32 v112, s100, v189
	v_add_u32_e32 v114, s100, v190
	v_mad_i64_i32 v[112:113], s[22:23], v112, s93, v[166:167]
	v_mad_i64_i32 v[114:115], s[22:23], v114, s93, v[166:167]
	global_load_dwordx4 v[136:139], v[112:113], off
	global_load_dwordx4 v[140:143], v[114:115], off
	s_min_u32 s100, s0, 1
	s_lshl_b32 s100, s100, 6
	v_add_u32_e32 v116, s100, v189
	v_add_u32_e32 v117, s100, v190
	v_mad_i64_i32 v[120:121], s[22:23], v116, s93, v[168:169]
	v_mad_i64_i32 v[124:125], s[22:23], v117, s93, v[168:169]
	s_nop 0
	global_load_dwordx4 v[112:115], v[124:125], off
	global_load_dwordx4 v[116:119], v[120:121], off
	s_nop 0
	global_load_dwordx4 v[120:123], v[120:121], off offset:256
	global_load_dwordx4 v[124:127], v[124:125], off offset:256
